# prologue adaLN GEMV: first row load of each 16-row step joins the other 15 (global load, single wait)
# speedup vs baseline: 1.0118x; 1.0042x over previous
; __device__ __forceinline__ void p0_mod(const float* c, const float* ada_w, const float* ada_b, float* MOD, LAS unsigned char* lds, int bid, int G, int tid, int wave, int lane) {
;     ...
;     for (int it = bid; it < DEPTH * (NADA / 192); it += G) {
;         const int layer = it / (NADA / 192), cg = it % (NADA / 192);
;         f32x4 a0 = {0.f, 0.f, 0.f, 0.f}, a1 = {0.f, 0.f, 0.f, 0.f};
;         if (lane < 48) { const float* wp = ada_w + (size_t)layer * DM * NADA + cg * 192 + lane * 4;
; #pragma unroll 16
;             for (int k = wave * 256; k < wave * 256 + 256; ++k) { const f32x4 w = *(const f32x4*)(wp + (size_t)k * NADA); a0 += cact[k] * w; a1 += cact[DM + k] * w; }
;             red[(wave * 2 + 0) * 48 + lane] = a0; red[(wave * 2 + 1) * 48 + lane] = a1; }
.LBB0_168:
	v_lshl_add_u64 v[18:19], v[16:17], 0, s[22:23]
	v_add_co_u32_e64 v22, s[6:7], s28, v18
	global_load_dwordx4 v[26:29], v[18:19], off
	s_nop 0
	v_addc_co_u32_e64 v23, s[6:7], 0, v19, s[6:7]
	v_add_co_u32_e64 v46, s[6:7], s30, v18
	v_mov_b32_e32 v25, s19
	s_nop 0
	v_addc_co_u32_e64 v47, s[6:7], 0, v19, s[6:7]
	v_add_co_u32_e64 v50, s[6:7], s31, v18
	ds_read_b128 v[30:33], v25
	ds_read_b128 v[34:37], v25 offset:16
	ds_read_b128 v[38:41], v25 offset:32
	v_addc_co_u32_e64 v51, s[6:7], 0, v19, s[6:7]
	v_add_co_u32_e64 v54, s[6:7], s34, v18
	s_waitcnt lgkmcnt(0)
	v_mov_b32_e32 v122, v37
	v_addc_co_u32_e64 v55, s[6:7], 0, v19, s[6:7]
	v_add_co_u32_e64 v58, s[6:7], s35, v18
	v_mov_b32_e32 v126, v41
	s_nop 0
	v_addc_co_u32_e64 v59, s[6:7], 0, v19, s[6:7]
	v_add_co_u32_e64 v62, s[6:7], s36, v18
	s_add_u32 s22, s22, 0xc0000
	s_nop 0
	v_addc_co_u32_e64 v63, s[6:7], 0, v19, s[6:7]
	v_add_co_u32_e64 v66, s[6:7], s37, v18
	s_addc_u32 s23, s23, 0
	s_nop 0
	v_addc_co_u32_e64 v67, s[6:7], 0, v19, s[6:7]
	v_add_co_u32_e64 v70, s[6:7], s40, v18
	s_add_i32 s19, s19, 64
	s_nop 0
	v_addc_co_u32_e64 v71, s[6:7], 0, v19, s[6:7]
	v_add_co_u32_e64 v74, s[6:7], s41, v18
	s_cmp_eq_u32 s22, 0xc00000
	s_nop 0
	v_addc_co_u32_e64 v75, s[6:7], 0, v19, s[6:7]
	v_add_co_u32_e64 v78, s[6:7], s42, v18
	v_addc_co_u32_e64 v79, s[6:7], 0, v19, s[6:7]
	v_add_co_u32_e64 v82, s[6:7], s43, v18
	s_nop 0
	v_addc_co_u32_e64 v83, s[6:7], 0, v19, s[6:7]
	v_add_co_u32_e64 v86, s[6:7], s44, v18
	s_nop 1
	v_addc_co_u32_e64 v87, s[6:7], 0, v19, s[6:7]
	v_add_co_u32_e64 v90, s[6:7], s45, v18
	s_nop 1
	v_addc_co_u32_e64 v91, s[6:7], 0, v19, s[6:7]
	v_add_co_u32_e64 v94, s[6:7], s46, v18
	s_nop 1
	v_addc_co_u32_e64 v95, s[6:7], 0, v19, s[6:7]
	v_add_co_u32_e64 v18, s[6:7], s47, v18
	s_nop 1
	v_addc_co_u32_e64 v19, s[6:7], 0, v19, s[6:7]
	flat_load_dwordx4 v[42:45], v[22:23]
	s_nop 0
	flat_load_dwordx4 v[46:49], v[46:47]
	s_nop 0
	flat_load_dwordx4 v[50:53], v[50:51]
	s_nop 0
	flat_load_dwordx4 v[54:57], v[54:55]
	s_nop 0
	flat_load_dwordx4 v[58:61], v[58:59]
	s_nop 0
	flat_load_dwordx4 v[62:65], v[62:63]
	s_nop 0
	flat_load_dwordx4 v[66:69], v[66:67]
	s_nop 0
	flat_load_dwordx4 v[70:73], v[70:71]
	s_nop 0
	flat_load_dwordx4 v[74:77], v[74:75]
	s_nop 0
	flat_load_dwordx4 v[78:81], v[78:79]
	s_nop 0
	flat_load_dwordx4 v[82:85], v[82:83]
	s_nop 0
	flat_load_dwordx4 v[86:89], v[86:87]
	s_nop 0
	flat_load_dwordx4 v[90:93], v[90:91]
	s_nop 0
	flat_load_dwordx4 v[94:97], v[94:95]
	s_nop 0
	flat_load_dwordx4 v[98:101], v[18:19]
	ds_read_b128 v[102:105], v25 offset:48
	ds_read_b128 v[106:109], v25 offset:8192
	ds_read_b128 v[110:113], v25 offset:8208
	ds_read_b128 v[114:117], v25 offset:8224
	ds_read_b128 v[118:121], v25 offset:8240
	v_mov_b32_e32 v18, v33
	s_waitcnt lgkmcnt(0)
	s_waitcnt vmcnt(0)
	v_pk_fma_f32 v[4:5], v[28:29], v[30:31], v[4:5] op_sel_hi:[1,0,1]
	v_pk_fma_f32 v[2:3], v[26:27], v[30:31], v[2:3] op_sel_hi:[1,0,1]
	v_pk_fma_f32 v[8:9], v[28:29], v[106:107], v[8:9] op_sel_hi:[1,0,1]
	v_pk_fma_f32 v[6:7], v[26:27], v[106:107], v[6:7] op_sel_hi:[1,0,1]
	v_mov_b32_e32 v22, v109
	v_mov_b32_e32 v124, v113
	v_mov_b32_e32 v128, v117
	v_mov_b32_e32 v130, v105
	v_mov_b32_e32 v132, v121
	s_waitcnt vmcnt(0)
; __device__ __forceinline__ void p0_mod(const float* c, const float* ada_w, const float* ada_b, float* MOD, LAS unsigned char* lds, int bid, int G, int tid, int wave, int lane) {
;     ...
;             for (int k = wave * 256; k < wave * 256 + 256; ++k) { const f32x4 w = *(const f32x4*)(wp + (size_t)k * NADA); a0 += cact[k] * w; a1 += cact[DM + k] * w; }
;             red[(wave * 2 + 0) * 48 + lane] = a0; red[(wave * 2 + 1) * 48 + lane] = a1; }
	v_pk_fma_f32 v[2:3], v[42:43], v[30:31], v[2:3] op_sel:[0,1,0]
	v_pk_fma_f32 v[4:5], v[44:45], v[30:31], v[4:5] op_sel:[0,1,0]
	v_pk_fma_f32 v[6:7], v[42:43], v[106:107], v[6:7] op_sel:[0,1,0]
	v_pk_fma_f32 v[8:9], v[44:45], v[106:107], v[8:9] op_sel:[0,1,0]
	v_pk_fma_f32 v[4:5], v[48:49], v[32:33], v[4:5] op_sel_hi:[1,0,1]
	v_pk_fma_f32 v[2:3], v[46:47], v[32:33], v[2:3] op_sel_hi:[1,0,1]
	v_pk_fma_f32 v[8:9], v[48:49], v[108:109], v[8:9] op_sel_hi:[1,0,1]
	v_pk_fma_f32 v[6:7], v[46:47], v[108:109], v[6:7] op_sel_hi:[1,0,1]
	v_pk_fma_f32 v[4:5], v[52:53], v[18:19], v[4:5] op_sel_hi:[1,0,1]
	v_pk_fma_f32 v[2:3], v[50:51], v[18:19], v[2:3] op_sel_hi:[1,0,1]
	v_pk_fma_f32 v[8:9], v[52:53], v[22:23], v[8:9] op_sel_hi:[1,0,1]
	v_pk_fma_f32 v[6:7], v[50:51], v[22:23], v[6:7] op_sel_hi:[1,0,1]
	v_pk_fma_f32 v[4:5], v[56:57], v[34:35], v[4:5] op_sel_hi:[1,0,1]
	v_pk_fma_f32 v[2:3], v[54:55], v[34:35], v[2:3] op_sel_hi:[1,0,1]
	v_pk_fma_f32 v[8:9], v[56:57], v[110:111], v[8:9] op_sel_hi:[1,0,1]
	v_pk_fma_f32 v[6:7], v[54:55], v[110:111], v[6:7] op_sel_hi:[1,0,1]
	v_pk_fma_f32 v[4:5], v[60:61], v[34:35], v[4:5] op_sel:[0,1,0]
	v_pk_fma_f32 v[2:3], v[58:59], v[34:35], v[2:3] op_sel:[0,1,0]
	v_pk_fma_f32 v[8:9], v[60:61], v[110:111], v[8:9] op_sel:[0,1,0]
	v_pk_fma_f32 v[6:7], v[58:59], v[110:111], v[6:7] op_sel:[0,1,0]
	v_pk_fma_f32 v[4:5], v[64:65], v[36:37], v[4:5] op_sel_hi:[1,0,1]
	v_pk_fma_f32 v[2:3], v[62:63], v[36:37], v[2:3] op_sel_hi:[1,0,1]
	v_pk_fma_f32 v[8:9], v[64:65], v[112:113], v[8:9] op_sel_hi:[1,0,1]
	v_pk_fma_f32 v[6:7], v[62:63], v[112:113], v[6:7] op_sel_hi:[1,0,1]
	v_pk_fma_f32 v[4:5], v[68:69], v[122:123], v[4:5] op_sel_hi:[1,0,1]
	v_pk_fma_f32 v[2:3], v[66:67], v[122:123], v[2:3] op_sel_hi:[1,0,1]
	v_pk_fma_f32 v[8:9], v[68:69], v[124:125], v[8:9] op_sel_hi:[1,0,1]
	v_pk_fma_f32 v[6:7], v[66:67], v[124:125], v[6:7] op_sel_hi:[1,0,1]
	v_pk_fma_f32 v[4:5], v[72:73], v[38:39], v[4:5] op_sel_hi:[1,0,1]
	v_pk_fma_f32 v[2:3], v[70:71], v[38:39], v[2:3] op_sel_hi:[1,0,1]
	v_pk_fma_f32 v[8:9], v[72:73], v[114:115], v[8:9] op_sel_hi:[1,0,1]
	v_pk_fma_f32 v[6:7], v[70:71], v[114:115], v[6:7] op_sel_hi:[1,0,1]
	v_pk_fma_f32 v[4:5], v[76:77], v[38:39], v[4:5] op_sel:[0,1,0]
	v_pk_fma_f32 v[2:3], v[74:75], v[38:39], v[2:3] op_sel:[0,1,0]
	v_pk_fma_f32 v[8:9], v[76:77], v[114:115], v[8:9] op_sel:[0,1,0]
	v_pk_fma_f32 v[6:7], v[74:75], v[114:115], v[6:7] op_sel:[0,1,0]
	v_pk_fma_f32 v[4:5], v[80:81], v[40:41], v[4:5] op_sel_hi:[1,0,1]
	v_pk_fma_f32 v[2:3], v[78:79], v[40:41], v[2:3] op_sel_hi:[1,0,1]
	v_pk_fma_f32 v[8:9], v[80:81], v[116:117], v[8:9] op_sel_hi:[1,0,1]
	v_pk_fma_f32 v[6:7], v[78:79], v[116:117], v[6:7] op_sel_hi:[1,0,1]
	v_pk_fma_f32 v[4:5], v[84:85], v[126:127], v[4:5] op_sel_hi:[1,0,1]
	v_pk_fma_f32 v[2:3], v[82:83], v[126:127], v[2:3] op_sel_hi:[1,0,1]
	v_pk_fma_f32 v[8:9], v[84:85], v[128:129], v[8:9] op_sel_hi:[1,0,1]
	v_pk_fma_f32 v[6:7], v[82:83], v[128:129], v[6:7] op_sel_hi:[1,0,1]
	v_pk_fma_f32 v[4:5], v[88:89], v[102:103], v[4:5] op_sel_hi:[1,0,1]
	v_pk_fma_f32 v[2:3], v[86:87], v[102:103], v[2:3] op_sel_hi:[1,0,1]
	v_pk_fma_f32 v[8:9], v[88:89], v[118:119], v[8:9] op_sel_hi:[1,0,1]
	v_pk_fma_f32 v[6:7], v[86:87], v[118:119], v[6:7] op_sel_hi:[1,0,1]
	v_pk_fma_f32 v[4:5], v[92:93], v[102:103], v[4:5] op_sel:[0,1,0]
	v_pk_fma_f32 v[2:3], v[90:91], v[102:103], v[2:3] op_sel:[0,1,0]
	v_pk_fma_f32 v[8:9], v[92:93], v[118:119], v[8:9] op_sel:[0,1,0]
	v_pk_fma_f32 v[6:7], v[90:91], v[118:119], v[6:7] op_sel:[0,1,0]
	v_pk_fma_f32 v[4:5], v[96:97], v[104:105], v[4:5] op_sel_hi:[1,0,1]
	v_pk_fma_f32 v[2:3], v[94:95], v[104:105], v[2:3] op_sel_hi:[1,0,1]
	v_pk_fma_f32 v[8:9], v[96:97], v[120:121], v[8:9] op_sel_hi:[1,0,1]
	v_pk_fma_f32 v[6:7], v[94:95], v[120:121], v[6:7] op_sel_hi:[1,0,1]
	v_pk_fma_f32 v[4:5], v[100:101], v[130:131], v[4:5] op_sel_hi:[1,0,1]
	v_pk_fma_f32 v[2:3], v[98:99], v[130:131], v[2:3] op_sel_hi:[1,0,1]
	v_pk_fma_f32 v[8:9], v[100:101], v[132:133], v[8:9] op_sel_hi:[1,0,1]
	v_pk_fma_f32 v[6:7], v[98:99], v[132:133], v[6:7] op_sel_hi:[1,0,1]
	s_cbranch_scc0 .LBB0_168
	ds_write_b128 v11, v[2:5] offset:16384
	ds_write_b128 v11, v[6:9] offset:17152
